# NA attention: defer K/V prefetch past bias loads, batch bias loads
# speedup vs baseline: 1.0737x; 1.0081x over previous
; #define AT_LOAD(KR, VR, ST) do { const int kb_ = step_kb((ST) < nst ? (ST) : nst - 1); \
;     _Pragma("unroll") for (int i = 0; i < 2; ++i) { KR[i] = *(const u32x4*)(K + (size_t)(kb_ + vd + 32 * i) * 64 + vc); \
;                                                     VR[i] = *(const u32x4*)(Vt + (size_t)(vd + 32 * i) * 2304 + kb_ + vc); } } while (0)
; #define AT_STORE(KR, VR, BUF) do { _Pragma("unroll") for (int i = 0; i < 2; ++i) { *(u32x4*)((BUF) + kwofs + i * 4096) = KR[i]; \
;     char* vp_ = (BUF) + 8192 + (vd + 32 * i) * 136 + vc * 2; \
;     *(uint2*)vp_ = make_uint2(VR[i][0], VR[i][1]); *(uint2*)(vp_ + 8) = make_uint2(VR[i][2], VR[i][3]); } } while (0)
; template <int MODE>
; DI void attn_block(const u16* __restrict__ Q, const u16* __restrict__ K, const u16* __restrict__ Vt, u16* __restrict__ Yout,
;                    int qpos0, int blk_lo, int blk_n, int w_lo, const float* rpb, float sink, bool has_sink, char* lds) {
;     ...
;     if (st + 1 < nst) {
;       AT_LOAD(kp, vp, st + 3);
;       __builtin_amdgcn_sched_barrier(0);
;       compute(st + 1, buf1);
;       AT_STORE(kq, vq, buf0);
;       __syncthreads();
.LBB0_773:
	s_or_b64 exec, exec, s[50:51]
	global_load_dwordx4 v[68:71], v[238:239], off
	global_load_dwordx4 v[72:75], v[240:241], off
	global_load_dwordx4 v[76:79], v[246:247], off
	global_load_dwordx4 v[80:83], v[248:249], off
	s_waitcnt vmcnt(7)
	ds_write_b128 v115, v[84:87]
	s_waitcnt vmcnt(6)
	ds_write2_b64 v117, v[88:89], v[90:91] offset1:1
	s_waitcnt vmcnt(5)
	ds_write_b128 v115, v[92:95] offset:4096
	s_waitcnt vmcnt(4)
	ds_write2_b64 v118, v[96:97], v[98:99] offset1:1
	s_waitcnt lgkmcnt(0)
	s_barrier

; #define MFMA(a, b, c) __builtin_amdgcn_mfma_f32_32x32x16_bf16((a), (b), (c), 0, 0, 0)
; template <int MODE>
; DI void attn_block(const u16* __restrict__ Q, const u16* __restrict__ K, const u16* __restrict__ Vt, u16* __restrict__ Yout,
;                    int qpos0, int blk_lo, int blk_n, int w_lo, const float* rpb, float sink, bool has_sink, char* lds) {
;     ...
;   auto compute = [&](const int st, const char* cur) {
;     const int kb = step_kb(st);
;     bool wave_on = true;
;     if (MODE == 1 && st >= 4) { const int rr = blk_lo + (st - 4); wave_on = rr >= w_lo && rr < w_lo + 8; }
;     if (wave_on) {
; #pragma unroll
;       for (int th = 0; th < 2; ++th) {
;         if (MODE == 0 && st >= 4 && 2 * (st - 4) + th >= blk_n) continue;
;         f32x16 S;
; #pragma unroll
;         for (int q = 0; q < 16; ++q) S[q] = 0.f;
; #pragma unroll
;         for (int ks = 0; ks < 4; ++ks) {
;           const s16x8 kf = *(const s16x8*)(cur + (th * 32 + r) * 128 + (((ks * 2 + h) ^ sw) << 4));
;           S = MFMA(kf, qf[ks], S);
;         }
;         if (st >= 4) {
;           if (MODE == 0) {
;             const int d0 = (qpos0 + r) - (kb + 32 * th + 4 * h);
; #pragma unroll
;             for (int reg = 0; reg < 16; ++reg) { const int d = d0 - ((reg & 3) + 8 * (reg >> 2)); if (d > 128 || d < -128) S[reg] = -INFINITY; }
;           } else if (MODE == 1) {
;             const int rr = blk_lo + (st - 4);
;             const float* brow = rpb + (rr - qr + 7) * 160 + 64;
;             const int cstart = min(max(qc - 8, 0), 48);
;             const int kc0 = 32 * th + 4 * h;
;             const float* bp = brow + (kc0 - qc + 15);
;             const int rel = kc0 - cstart;
; #pragma unroll
;             for (int reg = 0; reg < 16; ++reg) {
;               const int o = (reg & 3) + 8 * (reg >> 2);
;               const bool ok = (unsigned)(rel + o) < 16u;
;               const float tb = S[reg] + bp[o];
;               S[reg] = ok ? tb : -INFINITY;
;             }
;           }
.LBB0_775:
	s_add_i32 s61, s54, 4
	s_add_i32 s60, s54, 6
	s_cmp_lt_i32 s60, s18
	s_cselect_b32 s16, s60, s56
	s_lshl_b32 s17, s16, 6
	s_add_i32 s48, s16, s63
	s_addk_i32 s17, 0x800
	s_lshl_b32 s48, s48, 6
	s_cmp_lt_i32 s16, 4
	s_cselect_b32 s16, s17, s48
	v_add_u32_e32 v230, s16, v114
	v_ashrrev_i32_e32 v231, 31, v230
	s_ashr_i32 s17, s16, 31
	v_lshlrev_b64 v[230:231], 7, v[230:231]
	v_lshl_add_u64 v[236:237], s[16:17], 1, v[106:107]
	v_lshl_add_u64 v[230:231], v[14:15], 0, v[230:231]
	v_lshl_add_u64 v[232:233], v[236:237], 0, v[102:103]
	v_add_co_u32_e32 v234, vcc, 0x1000, v230
	v_lshl_add_u64 v[236:237], v[236:237], 0, v[104:105]
	s_nop 0
	v_addc_co_u32_e32 v235, vcc, 0, v231, vcc
	s_cmp_gt_u32 s61, 3
	s_cselect_b64 s[48:49], -1, 0
	s_cmp_lt_u32 s61, 4
	s_cselect_b64 s[50:51], -1, 0
	s_mov_b64 s[16:17], -1
	s_and_b64 vcc, exec, s[50:51]
	s_mov_b32 s57, s54
	s_cbranch_vccnz .LBB0_777
	s_add_i32 s16, s58, s54
	v_cmp_ge_i32_e32 vcc, s16, v120
	v_cmp_lt_i32_e64 s[16:17], s16, v122
	s_and_b64 s[16:17], vcc, s[16:17]
	s_add_i32 s57, s59, -4
	s_orn2_b64 s[16:17], s[16:17], exec
.LBB0_777:
	s_and_saveexec_b64 s[52:53], s[16:17]
	s_cbranch_execz .LBB0_783
	v_add_u32_e32 v138, v0, v124
	ds_read_b128 v[48:51], v138
	v_add_u32_e32 v139, v0, v125
	ds_read_b128 v[134:137], v139
	v_add_u32_e32 v140, v0, v126
	v_add_u32_e32 v145, v0, v127
	s_andn2_b64 vcc, exec, s[48:49]
	s_waitcnt lgkmcnt(1)
	v_mfma_f32_32x32x16_bf16 v[48:63], v[48:51], v[2:5], 0
	s_waitcnt lgkmcnt(0)
	v_mfma_f32_32x32x16_bf16 v[48:63], v[134:137], v[6:9], v[48:63]
	ds_read_b128 v[134:137], v140
	s_waitcnt lgkmcnt(0)
	v_mfma_f32_32x32x16_bf16 v[48:63], v[134:137], v[10:13], v[48:63]
	ds_read_b128 v[134:137], v145
	s_waitcnt lgkmcnt(0)
	v_mfma_f32_32x32x16_bf16 v[48:63], v[134:137], v[64:67], v[48:63]
	v_cndmask_b32_e64 v134, 0, 1, s[48:49]
	v_cmp_ne_u32_e64 s[16:17], 1, v134
	v_add_u32_e32 v134, s57, v123
	s_movk_i32 s57, 0xa0
	v_mul_lo_u32 v141, v134, s57
	s_cbranch_vccnz .LBB0_780
	v_add_u32_e32 v134, 0x460, v141
	v_ashrrev_i32_e32 v135, 31, v134
	v_lshl_add_u64 v[146:147], v[134:135], 2, v[108:109]
	global_load_dwordx4 v[214:217], v[146:147], off offset:316
	global_load_dwordx4 v[218:221], v[146:147], off offset:348
	global_load_dwordx4 v[222:225], v[146:147], off offset:380
	global_load_dwordx4 v[226:229], v[146:147], off offset:412
	v_readlane_b32 vcc_lo, v242, 45
	v_readlane_b32 vcc_hi, v242, 46
	s_waitcnt vmcnt(0)
	v_add_f32_e32 v48, v48, v214
	v_add_f32_e32 v49, v49, v215
	v_add_f32_e32 v50, v50, v216
	v_add_f32_e32 v51, v51, v217
	v_cndmask_b32_e32 v48, v210, v48, vcc
	v_readlane_b32 vcc_lo, v242, 47
	v_readlane_b32 vcc_hi, v242, 48
	v_add_f32_e32 v52, v52, v218
	v_add_f32_e32 v53, v53, v219
	v_add_f32_e32 v54, v54, v220
	v_add_f32_e32 v55, v55, v221
	v_cndmask_b32_e32 v49, v210, v49, vcc
	v_readlane_b32 vcc_lo, v242, 49
	v_readlane_b32 vcc_hi, v242, 50
	v_add_f32_e32 v56, v56, v222
	v_add_f32_e32 v57, v57, v223
	v_add_f32_e32 v58, v58, v224
	v_add_f32_e32 v59, v59, v225
	v_cndmask_b32_e32 v50, v210, v50, vcc
	v_readlane_b32 vcc_lo, v242, 51
	v_readlane_b32 vcc_hi, v242, 52
	v_cndmask_b32_e64 v57, v210, v57, s[64:65]
	v_cndmask_b32_e64 v58, v210, v58, s[66:67]
	v_cndmask_b32_e32 v51, v210, v51, vcc
	v_readlane_b32 vcc_lo, v242, 53
	v_readlane_b32 vcc_hi, v242, 54
	v_cndmask_b32_e64 v59, v210, v59, s[68:69]
	v_add_f32_e32 v60, v60, v226
	v_cndmask_b32_e32 v52, v210, v52, vcc
	v_readlane_b32 vcc_lo, v242, 55
	v_readlane_b32 vcc_hi, v242, 56
	v_add_f32_e32 v61, v61, v227
	v_add_f32_e32 v62, v62, v228
	v_cndmask_b32_e32 v53, v210, v53, vcc
	v_readlane_b32 vcc_lo, v242, 57
	v_readlane_b32 vcc_hi, v242, 58
	v_add_f32_e32 v63, v63, v229
	v_cndmask_b32_e64 v60, v210, v60, s[70:71]
	v_cndmask_b32_e32 v54, v210, v54, vcc
	v_readlane_b32 vcc_lo, v242, 59
	v_readlane_b32 vcc_hi, v242, 60
	v_cndmask_b32_e64 v61, v210, v61, s[72:73]
	v_cndmask_b32_e64 v62, v210, v62, s[74:75]
	v_cndmask_b32_e32 v55, v210, v55, vcc
	v_readlane_b32 vcc_lo, v242, 61
	v_readlane_b32 vcc_hi, v242, 62
	v_cndmask_b32_e64 v63, v210, v63, s[76:77]
	s_nop 0
	v_cndmask_b32_e32 v56, v210, v56, vcc
; template <int MODE>
; DI void attn_block(const u16* __restrict__ Q, const u16* __restrict__ K, const u16* __restrict__ Vt, u16* __restrict__ Yout,
;                    int qpos0, int blk_lo, int blk_n, int w_lo, const float* rpb, float sink, bool has_sink, char* lds) {
;     ...
;       for (int th = 0; th < 2; ++th) {
;         if (MODE == 0 && st >= 4 && 2 * (st - 4) + th >= blk_n) continue;
;         f32x16 S;
; #pragma unroll
;         for (int q = 0; q < 16; ++q) S[q] = 0.f;
; #pragma unroll
;         for (int ks = 0; ks < 4; ++ks) {
;           const s16x8 kf = *(const s16x8*)(cur + (th * 32 + r) * 128 + (((ks * 2 + h) ^ sw) << 4));
;           S = MFMA(kf, qf[ks], S);
;         }
;         if (st >= 4) {
;           if (MODE == 0) {
;             const int d0 = (qpos0 + r) - (kb + 32 * th + 4 * h);
; #pragma unroll
;             for (int reg = 0; reg < 16; ++reg) { const int d = d0 - ((reg & 3) + 8 * (reg >> 2)); if (d > 128 || d < -128) S[reg] = -INFINITY; }
;           } else if (MODE == 1) {
;             const int rr = blk_lo + (st - 4);
;             const float* brow = rpb + (rr - qr + 7) * 160 + 64;
;             const int cstart = min(max(qc - 8, 0), 48);
;             const int kc0 = 32 * th + 4 * h;
;             const float* bp = brow + (kc0 - qc + 15);
;             const int rel = kc0 - cstart;
; #pragma unroll
;             for (int reg = 0; reg < 16; ++reg) {
;               const int o = (reg & 3) + 8 * (reg >> 2);
;               const bool ok = (unsigned)(rel + o) < 16u;
;               const float tb = S[reg] + bp[o];
;               S[reg] = ok ? tb : -INFINITY;
;             }
;           }
;         }
;         float mx = S[0];
; #pragma unroll
;         for (int reg = 1; reg < 16; ++reg) mx = fmaxf(mx, S[reg]);
;         mx = fmaxf(mx, __shfl_xor(mx, 32));
;         const float mnew = fmaxf(mrun, mx);
;         const float alpha = __expf(mrun - mnew);
;         float ps = 0.f;
; #pragma unroll
;         for (int reg = 0; reg < 16; ++reg) { S[reg] = __expf(S[reg] - mnew); ps += S[reg]; }
;         lrun = lrun * alpha + ps;
;         mrun = mnew;
; #pragma unroll
;         for (int q = 0; q < 16; ++q) { O0[q] *= alpha; O1[q] *= alpha; }
; #pragma unroll
;         for (int s2 = 0; s2 < 2; ++s2) {
;           union { s16x8 v; unsigned u[4]; } pf;
; #pragma unroll
.LBB0_780:
	v_cmp_lt_i32_e32 vcc, v187, v186
	s_nop 4
	v_max_f32_e32 v135, v48, v48
	v_cndmask_b32_e32 v134, v185, v187, vcc
	v_lshlrev_b32_e32 v137, 2, v134
	v_max_f32_e32 v134, v49, v49
	v_max_f32_e32 v134, v135, v134
	v_max3_f32 v134, v134, v50, v51
	v_max3_f32 v134, v134, v52, v53
	v_max3_f32 v134, v134, v54, v55
	v_max3_f32 v134, v134, v56, v57
	v_max3_f32 v134, v134, v58, v59
	v_max3_f32 v134, v134, v60, v61
	v_max3_f32 v134, v134, v62, v63
	ds_bpermute_b32 v135, v137, v134
	s_and_b64 vcc, exec, s[16:17]
	s_waitcnt lgkmcnt(0)
	v_max3_f32 v136, v112, v134, v135
	v_sub_f32_e32 v48, v48, v136
	v_mul_f32_e32 v48, 0x3fb8aa3b, v48
	v_exp_f32_e32 v146, v48
	v_sub_f32_e32 v48, v49, v136
	v_mul_f32_e32 v48, 0x3fb8aa3b, v48
	v_exp_f32_e32 v147, v48
	v_sub_f32_e32 v48, v50, v136
	v_mul_f32_e32 v48, 0x3fb8aa3b, v48
	v_exp_f32_e32 v148, v48
	v_sub_f32_e32 v48, v51, v136
	v_mul_f32_e32 v48, 0x3fb8aa3b, v48
	v_exp_f32_e32 v149, v48
	v_sub_f32_e32 v48, v52, v136
	v_mul_f32_e32 v48, 0x3fb8aa3b, v48
	v_exp_f32_e32 v150, v48
	v_sub_f32_e32 v48, v53, v136
	v_mul_f32_e32 v48, 0x3fb8aa3b, v48
	v_exp_f32_e32 v151, v48
	v_sub_f32_e32 v48, v54, v136
	v_mul_f32_e32 v48, 0x3fb8aa3b, v48
	v_exp_f32_e32 v152, v48
	v_sub_f32_e32 v48, v55, v136
	v_mul_f32_e32 v48, 0x3fb8aa3b, v48
	v_exp_f32_e32 v153, v48
	v_sub_f32_e32 v48, v56, v136
	v_mul_f32_e32 v48, 0x3fb8aa3b, v48
	v_exp_f32_e32 v154, v48
	v_sub_f32_e32 v48, v57, v136
	v_mul_f32_e32 v48, 0x3fb8aa3b, v48
	v_exp_f32_e32 v155, v48
	v_sub_f32_e32 v48, v58, v136
	v_mul_f32_e32 v48, 0x3fb8aa3b, v48
	v_exp_f32_e32 v156, v48
	v_sub_f32_e32 v48, v59, v136
	v_mul_f32_e32 v48, 0x3fb8aa3b, v48
	v_exp_f32_e32 v157, v48
	v_sub_f32_e32 v48, v60, v136
	v_mul_f32_e32 v48, 0x3fb8aa3b, v48
	v_exp_f32_e32 v158, v48
	v_sub_f32_e32 v48, v61, v136
	v_mul_f32_e32 v48, 0x3fb8aa3b, v48
	v_exp_f32_e32 v159, v48
	v_sub_f32_e32 v48, v62, v136
	v_add_u32_e32 v60, v128, v121
	v_mul_f32_e32 v48, 0x3fb8aa3b, v48
	v_add_u32_e32 v135, 0x2000, v60
	v_add_u32_e32 v134, 0x3000, v60
	v_exp_f32_e32 v160, v48
	v_sub_f32_e32 v48, v63, v136
	ds_read2_b64 v[52:55], v135 offset1:2
	ds_read2_b64 v[56:59], v135 offset0:4 offset1:6
	ds_read2_b64 v[60:63], v134 offset0:32 offset1:34
	v_sub_f32_e32 v112, v112, v136
	v_mul_f32_e32 v112, 0x3fb8aa3b, v112
	v_exp_f32_e32 v112, v112
	v_mul_f32_e32 v48, 0x3fb8aa3b, v48
	v_exp_f32_e32 v161, v48
	v_cvt_pk_bf16_f32 v51, v152, v153
	v_pk_mul_f32 v[46:47], v[46:47], v[112:113] op_sel_hi:[1,0]
	v_pk_mul_f32 v[44:45], v[44:45], v[112:113] op_sel_hi:[1,0]
	v_pk_mul_f32 v[42:43], v[42:43], v[112:113] op_sel_hi:[1,0]
	v_pk_mul_f32 v[40:41], v[40:41], v[112:113] op_sel_hi:[1,0]
	v_pk_mul_f32 v[38:39], v[38:39], v[112:113] op_sel_hi:[1,0]
	v_pk_mul_f32 v[36:37], v[36:37], v[112:113] op_sel_hi:[1,0]
	v_pk_mul_f32 v[34:35], v[34:35], v[112:113] op_sel_hi:[1,0]
	v_pk_mul_f32 v[32:33], v[32:33], v[112:113] op_sel_hi:[1,0]
	v_cvt_pk_bf16_f32 v50, v150, v151
	v_cvt_pk_bf16_f32 v49, v148, v149
	v_cvt_pk_bf16_f32 v48, v146, v147
	v_pk_mul_f32 v[30:31], v[30:31], v[112:113] op_sel_hi:[1,0]
	v_pk_mul_f32 v[28:29], v[28:29], v[112:113] op_sel_hi:[1,0]
	v_pk_mul_f32 v[26:27], v[26:27], v[112:113] op_sel_hi:[1,0]
	v_pk_mul_f32 v[24:25], v[24:25], v[112:113] op_sel_hi:[1,0]
	v_pk_mul_f32 v[22:23], v[22:23], v[112:113] op_sel_hi:[1,0]
	v_pk_mul_f32 v[20:21], v[20:21], v[112:113] op_sel_hi:[1,0]
	v_pk_mul_f32 v[18:19], v[18:19], v[112:113] op_sel_hi:[1,0]
	v_pk_mul_f32 v[16:17], v[16:17], v[112:113] op_sel_hi:[1,0]
	s_waitcnt lgkmcnt(2)
	v_mfma_f32_32x32x16_bf16 v[32:47], v[52:55], v[48:51], v[32:47]
	ds_read2_b64 v[52:55], v134 offset0:36 offset1:38
	ds_read_b128 v[162:165], v139 offset:4096
	s_waitcnt lgkmcnt(2)
	v_mfma_f32_32x32x16_bf16 v[16:31], v[60:63], v[48:51], v[16:31]
	v_cvt_pk_bf16_f32 v51, v160, v161
	v_cvt_pk_bf16_f32 v50, v158, v159
	v_cvt_pk_bf16_f32 v49, v156, v157
	v_cvt_pk_bf16_f32 v48, v154, v155
	s_nop 1
	v_mfma_f32_32x32x16_bf16 v[32:47], v[56:59], v[48:51], v[32:47]
	s_waitcnt lgkmcnt(1)
	v_mfma_f32_32x32x16_bf16 v[16:31], v[52:55], v[48:51], v[16:31]
	ds_read_b128 v[48:51], v138 offset:4096
	s_waitcnt lgkmcnt(0)
	v_mfma_f32_32x32x16_bf16 v[48:63], v[48:51], v[2:5], 0
	v_mfma_f32_32x32x16_bf16 v[48:63], v[162:165], v[6:9], v[48:63]
	ds_read_b128 v[162:165], v140 offset:4096
	s_waitcnt lgkmcnt(0)
	v_mfma_f32_32x32x16_bf16 v[48:63], v[162:165], v[10:13], v[48:63]
	ds_read_b128 v[162:165], v145 offset:4096
	s_waitcnt lgkmcnt(0)
	v_mfma_f32_32x32x16_bf16 v[48:63], v[162:165], v[64:67], v[48:63]
	s_cbranch_vccnz .LBB0_782
	v_add_u32_e32 v138, 0x460, v141
	v_ashrrev_i32_e32 v139, 31, v138
	v_lshl_add_u64 v[162:163], v[138:139], 2, v[110:111]
	global_load_dwordx4 v[214:217], v[162:163], off offset:444
	global_load_dwordx4 v[218:221], v[162:163], off offset:476
	global_load_dwordx4 v[222:225], v[162:163], off offset:508
	global_load_dwordx4 v[226:229], v[162:163], off offset:540
	s_waitcnt vmcnt(0)
	s_nop 5
	v_add_f32_e32 v48, v48, v214
	v_add_f32_e32 v49, v49, v215
	v_add_f32_e32 v50, v50, v216
	v_add_f32_e32 v51, v51, v217
	v_cndmask_b32_e64 v48, v210, v48, s[46:47]
	v_cndmask_b32_e64 v49, v210, v49, s[80:81]
	v_cndmask_b32_e64 v50, v210, v50, s[82:83]
	v_cndmask_b32_e64 v51, v210, v51, s[84:85]
	v_add_f32_e32 v52, v52, v218
	v_add_f32_e32 v53, v53, v219
	v_add_f32_e32 v54, v54, v220
	v_add_f32_e32 v55, v55, v221
	v_cndmask_b32_e64 v52, v210, v52, s[86:87]
	v_cndmask_b32_e64 v53, v210, v53, s[88:89]
	v_cndmask_b32_e64 v54, v210, v54, s[90:91]
	v_cndmask_b32_e64 v55, v210, v55, s[92:93]
	v_add_f32_e32 v56, v56, v222
	v_add_f32_e32 v57, v57, v223
	v_add_f32_e32 v58, v58, v224
	v_add_f32_e32 v59, v59, v225
	v_cndmask_b32_e64 v56, v210, v56, s[94:95]
	v_cndmask_b32_e64 v57, v210, v57, s[96:97]
	v_cndmask_b32_e64 v58, v210, v58, s[40:41]
	v_cndmask_b32_e64 v59, v210, v59, s[6:7]
	v_add_f32_e32 v60, v60, v226
	v_add_f32_e32 v61, v61, v227
	v_add_f32_e32 v62, v62, v228
	v_add_f32_e32 v63, v63, v229
	v_cndmask_b32_e64 v60, v210, v60, s[8:9]
	v_cndmask_b32_e64 v61, v210, v61, s[10:11]
	v_cndmask_b32_e64 v62, v210, v62, s[12:13]
	v_cndmask_b32_e64 v63, v210, v63, s[14:15]

; #define AT_LOAD(KR, VR, ST) do { const int kb_ = step_kb((ST) < nst ? (ST) : nst - 1); \
;     _Pragma("unroll") for (int i = 0; i < 2; ++i) { KR[i] = *(const u32x4*)(K + (size_t)(kb_ + vd + 32 * i) * 64 + vc); \
;                                                     VR[i] = *(const u32x4*)(Vt + (size_t)(vd + 32 * i) * 2304 + kb_ + vc); } } while (0)
; #define AT_STORE(KR, VR, BUF) do { _Pragma("unroll") for (int i = 0; i < 2; ++i) { *(u32x4*)((BUF) + kwofs + i * 4096) = KR[i]; \
;     char* vp_ = (BUF) + 8192 + (vd + 32 * i) * 136 + vc * 2; \
;     *(uint2*)vp_ = make_uint2(VR[i][0], VR[i][1]); *(uint2*)(vp_ + 8) = make_uint2(VR[i][2], VR[i][3]); } } while (0)
; template <int MODE>
; DI void attn_block(const u16* __restrict__ Q, const u16* __restrict__ K, const u16* __restrict__ Vt, u16* __restrict__ Yout,
;                    int qpos0, int blk_lo, int blk_n, int w_lo, const float* rpb, float sink, bool has_sink, char* lds) {
;     ...
;     AT_STORE(kp, vp, buf1);
;     __syncthreads();
;     if (st + 1 < nst) {
;       AT_LOAD(kp, vp, st + 3);
.LBB0_783:
	s_or_b64 exec, exec, s[52:53]
	global_load_dwordx4 v[84:87], v[230:231], off
	global_load_dwordx4 v[88:91], v[232:233], off
	global_load_dwordx4 v[92:95], v[234:235], off
	global_load_dwordx4 v[96:99], v[236:237], off
	v_add_u32_e32 v48, 0x6200, v116
	s_waitcnt vmcnt(7)
	ds_write_b128 v115, v[68:71] offset:16896
	s_waitcnt vmcnt(6)
	ds_write2_b64 v48, v[72:73], v[74:75] offset1:1
	s_waitcnt vmcnt(5)
	ds_write_b128 v115, v[76:79] offset:20992
	v_add_u32_e32 v48, 0x7300, v116
	s_cmp_ge_i32 s61, s56
	s_waitcnt vmcnt(4)
	ds_write2_b64 v48, v[80:81], v[82:83] offset1:1
	s_waitcnt lgkmcnt(0)
	s_barrier
	s_cbranch_scc1 .LBB0_774
	s_add_i32 s16, s54, 7
	s_cmp_lt_i32 s16, s18
	s_cselect_b32 s16, s16, s56
	s_lshl_b32 s17, s16, 6
	s_add_i32 s52, s16, s63
	s_addk_i32 s17, 0x800
	s_lshl_b32 s52, s52, 6
	s_cmp_lt_i32 s16, 4
	s_cselect_b32 s16, s17, s52
	v_add_u32_e32 v238, s16, v114
	v_ashrrev_i32_e32 v239, 31, v238
	s_ashr_i32 s17, s16, 31
	v_lshlrev_b64 v[238:239], 7, v[238:239]
	v_lshl_add_u64 v[248:249], s[16:17], 1, v[106:107]
	v_lshl_add_u64 v[238:239], v[14:15], 0, v[238:239]
	v_lshl_add_u64 v[240:241], v[248:249], 0, v[102:103]
	v_add_co_u32_e32 v246, vcc, 0x1000, v238
	v_lshl_add_u64 v[248:249], v[248:249], 0, v[104:105]
	s_nop 0
	v_addc_co_u32_e32 v247, vcc, 0, v239, vcc
	s_andn2_b64 vcc, exec, s[50:51]
	s_cbranch_vccnz .LBB0_786
	s_add_i32 s61, s54, 1
	s_mov_b64 s[52:53], -1
	s_cbranch_execz .LBB0_787
	s_branch .LBB0_788

; #define MFMA(a, b, c) __builtin_amdgcn_mfma_f32_32x32x16_bf16((a), (b), (c), 0, 0, 0)
; template <int MODE>
; DI void attn_block(const u16* __restrict__ Q, const u16* __restrict__ K, const u16* __restrict__ Vt, u16* __restrict__ Yout,
;                    int qpos0, int blk_lo, int blk_n, int w_lo, const float* rpb, float sink, bool has_sink, char* lds) {
;     ...
;   auto compute = [&](const int st, const char* cur) {
;     const int kb = step_kb(st);
;     bool wave_on = true;
;     if (MODE == 1 && st >= 4) { const int rr = blk_lo + (st - 4); wave_on = rr >= w_lo && rr < w_lo + 8; }
;     if (wave_on) {
; #pragma unroll
;       for (int th = 0; th < 2; ++th) {
;         if (MODE == 0 && st >= 4 && 2 * (st - 4) + th >= blk_n) continue;
;         f32x16 S;
; #pragma unroll
;         for (int q = 0; q < 16; ++q) S[q] = 0.f;
; #pragma unroll
;         for (int ks = 0; ks < 4; ++ks) {
;           const s16x8 kf = *(const s16x8*)(cur + (th * 32 + r) * 128 + (((ks * 2 + h) ^ sw) << 4));
;           S = MFMA(kf, qf[ks], S);
;         }
;         if (st >= 4) {
;           if (MODE == 0) {
;             const int d0 = (qpos0 + r) - (kb + 32 * th + 4 * h);
; #pragma unroll
;             for (int reg = 0; reg < 16; ++reg) { const int d = d0 - ((reg & 3) + 8 * (reg >> 2)); if (d > 128 || d < -128) S[reg] = -INFINITY; }
;           } else if (MODE == 1) {
;             const int rr = blk_lo + (st - 4);
;             const float* brow = rpb + (rr - qr + 7) * 160 + 64;
;             const int cstart = min(max(qc - 8, 0), 48);
;             const int kc0 = 32 * th + 4 * h;
;             const float* bp = brow + (kc0 - qc + 15);
;             const int rel = kc0 - cstart;
; #pragma unroll
;             for (int reg = 0; reg < 16; ++reg) {
;               const int o = (reg & 3) + 8 * (reg >> 2);
;               const bool ok = (unsigned)(rel + o) < 16u;
;               const float tb = S[reg] + bp[o];
;               S[reg] = ok ? tb : -INFINITY;
;             }
;           }
.LBB0_788:
	s_and_saveexec_b64 s[50:51], s[52:53]
	s_cbranch_execz .LBB0_773
	v_add_u32_e32 v138, v0, v124
	ds_read_b128 v[48:51], v138 offset:16896
	v_add_u32_e32 v139, v0, v125
	ds_read_b128 v[134:137], v139 offset:16896
	v_add_u32_e32 v140, v0, v126
	v_add_u32_e32 v145, v0, v127
	s_andn2_b64 vcc, exec, s[48:49]
	s_waitcnt lgkmcnt(1)
	v_mfma_f32_32x32x16_bf16 v[48:63], v[48:51], v[2:5], 0
	s_waitcnt lgkmcnt(0)
	v_mfma_f32_32x32x16_bf16 v[48:63], v[134:137], v[6:9], v[48:63]
	ds_read_b128 v[134:137], v140 offset:16896
	s_waitcnt lgkmcnt(0)
	v_mfma_f32_32x32x16_bf16 v[48:63], v[134:137], v[10:13], v[48:63]
	ds_read_b128 v[134:137], v145 offset:16896
	s_waitcnt lgkmcnt(0)
	v_mfma_f32_32x32x16_bf16 v[48:63], v[134:137], v[64:67], v[48:63]
	v_cndmask_b32_e64 v134, 0, 1, s[48:49]
	v_cmp_ne_u32_e64 s[16:17], 1, v134
	v_add_u32_e32 v134, s61, v123
	s_movk_i32 s48, 0xa0
	v_mul_lo_u32 v141, v134, s48
	s_cbranch_vccnz .LBB0_791
	v_add_u32_e32 v134, 0x460, v141
	v_ashrrev_i32_e32 v135, 31, v134
	v_lshl_add_u64 v[146:147], v[134:135], 2, v[108:109]
	global_load_dwordx4 v[214:217], v[146:147], off offset:316
	global_load_dwordx4 v[218:221], v[146:147], off offset:348
	global_load_dwordx4 v[222:225], v[146:147], off offset:380
	global_load_dwordx4 v[226:229], v[146:147], off offset:412
	v_readlane_b32 s48, v242, 45
	v_readlane_b32 s49, v242, 46
	s_waitcnt vmcnt(0)
	v_add_f32_e32 v48, v48, v214
	v_add_f32_e32 v49, v49, v215
	v_add_f32_e32 v50, v50, v216
	v_add_f32_e32 v51, v51, v217
	v_cndmask_b32_e64 v48, v210, v48, s[48:49]
	v_readlane_b32 s48, v242, 47
	v_readlane_b32 s49, v242, 48
	v_add_f32_e32 v52, v52, v218
	v_add_f32_e32 v53, v53, v219
	v_add_f32_e32 v54, v54, v220
	v_add_f32_e32 v55, v55, v221
	v_cndmask_b32_e64 v49, v210, v49, s[48:49]
	v_readlane_b32 s48, v242, 49
	v_readlane_b32 s49, v242, 50
	v_add_f32_e32 v56, v56, v222
	v_add_f32_e32 v57, v57, v223
	v_add_f32_e32 v58, v58, v224
	v_add_f32_e32 v59, v59, v225
	v_cndmask_b32_e64 v50, v210, v50, s[48:49]
	v_readlane_b32 s48, v242, 51
	v_readlane_b32 s49, v242, 52
	v_cndmask_b32_e64 v57, v210, v57, s[64:65]
	v_cndmask_b32_e64 v58, v210, v58, s[66:67]
	v_cndmask_b32_e64 v51, v210, v51, s[48:49]
	v_readlane_b32 s48, v242, 53
	v_readlane_b32 s49, v242, 54
	v_cndmask_b32_e64 v59, v210, v59, s[68:69]
	v_add_f32_e32 v60, v60, v226
	v_cndmask_b32_e64 v52, v210, v52, s[48:49]
	v_readlane_b32 s48, v242, 55
	v_readlane_b32 s49, v242, 56
	v_add_f32_e32 v61, v61, v227
	v_add_f32_e32 v62, v62, v228
	v_cndmask_b32_e64 v53, v210, v53, s[48:49]
	v_readlane_b32 s48, v242, 57
	v_readlane_b32 s49, v242, 58
	v_add_f32_e32 v63, v63, v229
	v_cndmask_b32_e64 v60, v210, v60, s[70:71]
	v_cndmask_b32_e64 v54, v210, v54, s[48:49]
	v_readlane_b32 s48, v242, 59
	v_readlane_b32 s49, v242, 60
	v_cndmask_b32_e64 v61, v210, v61, s[72:73]
	v_cndmask_b32_e64 v62, v210, v62, s[74:75]
	v_cndmask_b32_e64 v55, v210, v55, s[48:49]
	v_readlane_b32 s48, v242, 61
	v_readlane_b32 s49, v242, 62
	v_cndmask_b32_e64 v63, v210, v63, s[76:77]
	s_nop 0
	v_cndmask_b32_e64 v56, v210, v56, s[48:49]
; template <int MODE>
; DI void attn_block(const u16* __restrict__ Q, const u16* __restrict__ K, const u16* __restrict__ Vt, u16* __restrict__ Yout,
;                    int qpos0, int blk_lo, int blk_n, int w_lo, const float* rpb, float sink, bool has_sink, char* lds) {
;     ...
;       for (int th = 0; th < 2; ++th) {
;         if (MODE == 0 && st >= 4 && 2 * (st - 4) + th >= blk_n) continue;
;         f32x16 S;
; #pragma unroll
;         for (int q = 0; q < 16; ++q) S[q] = 0.f;
; #pragma unroll
;         for (int ks = 0; ks < 4; ++ks) {
;           const s16x8 kf = *(const s16x8*)(cur + (th * 32 + r) * 128 + (((ks * 2 + h) ^ sw) << 4));
;           S = MFMA(kf, qf[ks], S);
;         }
;         if (st >= 4) {
;           if (MODE == 0) {
;             const int d0 = (qpos0 + r) - (kb + 32 * th + 4 * h);
; #pragma unroll
;             for (int reg = 0; reg < 16; ++reg) { const int d = d0 - ((reg & 3) + 8 * (reg >> 2)); if (d > 128 || d < -128) S[reg] = -INFINITY; }
;           } else if (MODE == 1) {
;             const int rr = blk_lo + (st - 4);
;             const float* brow = rpb + (rr - qr + 7) * 160 + 64;
;             const int cstart = min(max(qc - 8, 0), 48);
;             const int kc0 = 32 * th + 4 * h;
;             const float* bp = brow + (kc0 - qc + 15);
;             const int rel = kc0 - cstart;
; #pragma unroll
;             for (int reg = 0; reg < 16; ++reg) {
;               const int o = (reg & 3) + 8 * (reg >> 2);
;               const bool ok = (unsigned)(rel + o) < 16u;
;               const float tb = S[reg] + bp[o];
;               S[reg] = ok ? tb : -INFINITY;
;             }
;           }
;         }
;         float mx = S[0];
; #pragma unroll
;         for (int reg = 1; reg < 16; ++reg) mx = fmaxf(mx, S[reg]);
;         mx = fmaxf(mx, __shfl_xor(mx, 32));
;         const float mnew = fmaxf(mrun, mx);
;         const float alpha = __expf(mrun - mnew);
;         float ps = 0.f;
; #pragma unroll
;         for (int reg = 0; reg < 16; ++reg) { S[reg] = __expf(S[reg] - mnew); ps += S[reg]; }
;         lrun = lrun * alpha + ps;
;         mrun = mnew;
; #pragma unroll
;         for (int q = 0; q < 16; ++q) { O0[q] *= alpha; O1[q] *= alpha; }
; #pragma unroll
;         for (int s2 = 0; s2 < 2; ++s2) {
;           union { s16x8 v; unsigned u[4]; } pf;
; #pragma unroll
.LBB0_791:
	v_cmp_lt_i32_e32 vcc, v187, v186
	s_nop 4
	v_max_f32_e32 v135, v48, v48
	v_cndmask_b32_e32 v134, v185, v187, vcc
	v_lshlrev_b32_e32 v137, 2, v134
	v_max_f32_e32 v134, v49, v49
	v_max_f32_e32 v134, v135, v134
	v_max3_f32 v134, v134, v50, v51
	v_max3_f32 v134, v134, v52, v53
	v_max3_f32 v134, v134, v54, v55
	v_max3_f32 v134, v134, v56, v57
	v_max3_f32 v134, v134, v58, v59
	v_max3_f32 v134, v134, v60, v61
	v_max3_f32 v134, v134, v62, v63
	ds_bpermute_b32 v135, v137, v134
	s_and_b64 vcc, exec, s[16:17]
	s_waitcnt lgkmcnt(0)
	v_max3_f32 v136, v112, v134, v135
	v_sub_f32_e32 v48, v48, v136
	v_mul_f32_e32 v48, 0x3fb8aa3b, v48
	v_exp_f32_e32 v146, v48
	v_sub_f32_e32 v48, v49, v136
	v_mul_f32_e32 v48, 0x3fb8aa3b, v48
	v_exp_f32_e32 v147, v48
	v_sub_f32_e32 v48, v50, v136
	v_mul_f32_e32 v48, 0x3fb8aa3b, v48
	v_exp_f32_e32 v148, v48
	v_sub_f32_e32 v48, v51, v136
	v_mul_f32_e32 v48, 0x3fb8aa3b, v48
	v_exp_f32_e32 v149, v48
	v_sub_f32_e32 v48, v52, v136
	v_mul_f32_e32 v48, 0x3fb8aa3b, v48
	v_exp_f32_e32 v150, v48
	v_sub_f32_e32 v48, v53, v136
	v_mul_f32_e32 v48, 0x3fb8aa3b, v48
	v_exp_f32_e32 v151, v48
	v_sub_f32_e32 v48, v54, v136
	v_mul_f32_e32 v48, 0x3fb8aa3b, v48
	v_exp_f32_e32 v152, v48
	v_sub_f32_e32 v48, v55, v136
	v_mul_f32_e32 v48, 0x3fb8aa3b, v48
	v_exp_f32_e32 v153, v48
	v_sub_f32_e32 v48, v56, v136
	v_mul_f32_e32 v48, 0x3fb8aa3b, v48
	v_exp_f32_e32 v154, v48
	v_sub_f32_e32 v48, v57, v136
	v_mul_f32_e32 v48, 0x3fb8aa3b, v48
	v_exp_f32_e32 v155, v48
	v_sub_f32_e32 v48, v58, v136
	v_mul_f32_e32 v48, 0x3fb8aa3b, v48
	v_exp_f32_e32 v156, v48
	v_sub_f32_e32 v48, v59, v136
	v_mul_f32_e32 v48, 0x3fb8aa3b, v48
	v_exp_f32_e32 v157, v48
	v_sub_f32_e32 v48, v60, v136
	v_mul_f32_e32 v48, 0x3fb8aa3b, v48
	v_exp_f32_e32 v158, v48
	v_sub_f32_e32 v48, v61, v136
	v_mul_f32_e32 v48, 0x3fb8aa3b, v48
	v_exp_f32_e32 v159, v48
	v_sub_f32_e32 v48, v62, v136
	v_add_u32_e32 v60, v128, v121
	v_mul_f32_e32 v48, 0x3fb8aa3b, v48
	v_add_u32_e32 v135, 0x6000, v60
	v_add_u32_e32 v134, 0x7000, v60
	v_exp_f32_e32 v160, v48
	v_sub_f32_e32 v48, v63, v136
	ds_read2_b64 v[52:55], v135 offset0:64 offset1:66
	ds_read2_b64 v[56:59], v135 offset0:68 offset1:70
	ds_read2_b64 v[60:63], v134 offset0:96 offset1:98
	v_sub_f32_e32 v112, v112, v136
	v_mul_f32_e32 v112, 0x3fb8aa3b, v112
	v_exp_f32_e32 v112, v112
	v_mul_f32_e32 v48, 0x3fb8aa3b, v48
	v_exp_f32_e32 v161, v48
	v_cvt_pk_bf16_f32 v51, v152, v153
	v_pk_mul_f32 v[46:47], v[46:47], v[112:113] op_sel_hi:[1,0]
	v_pk_mul_f32 v[44:45], v[44:45], v[112:113] op_sel_hi:[1,0]
	v_pk_mul_f32 v[42:43], v[42:43], v[112:113] op_sel_hi:[1,0]
	v_pk_mul_f32 v[40:41], v[40:41], v[112:113] op_sel_hi:[1,0]
	v_pk_mul_f32 v[38:39], v[38:39], v[112:113] op_sel_hi:[1,0]
	v_pk_mul_f32 v[36:37], v[36:37], v[112:113] op_sel_hi:[1,0]
	v_pk_mul_f32 v[34:35], v[34:35], v[112:113] op_sel_hi:[1,0]
	v_pk_mul_f32 v[32:33], v[32:33], v[112:113] op_sel_hi:[1,0]
	v_cvt_pk_bf16_f32 v50, v150, v151
	v_cvt_pk_bf16_f32 v49, v148, v149
	v_cvt_pk_bf16_f32 v48, v146, v147
	v_pk_mul_f32 v[30:31], v[30:31], v[112:113] op_sel_hi:[1,0]
	v_pk_mul_f32 v[28:29], v[28:29], v[112:113] op_sel_hi:[1,0]
	v_pk_mul_f32 v[26:27], v[26:27], v[112:113] op_sel_hi:[1,0]
	v_pk_mul_f32 v[24:25], v[24:25], v[112:113] op_sel_hi:[1,0]
	v_pk_mul_f32 v[22:23], v[22:23], v[112:113] op_sel_hi:[1,0]
	v_pk_mul_f32 v[20:21], v[20:21], v[112:113] op_sel_hi:[1,0]
	v_pk_mul_f32 v[18:19], v[18:19], v[112:113] op_sel_hi:[1,0]
	v_pk_mul_f32 v[16:17], v[16:17], v[112:113] op_sel_hi:[1,0]
	s_waitcnt lgkmcnt(2)
	v_mfma_f32_32x32x16_bf16 v[32:47], v[52:55], v[48:51], v[32:47]
	ds_read2_b64 v[52:55], v134 offset0:100 offset1:102
	ds_read_b128 v[162:165], v139 offset:20992
	s_waitcnt lgkmcnt(2)
	v_mfma_f32_32x32x16_bf16 v[16:31], v[60:63], v[48:51], v[16:31]
	v_cvt_pk_bf16_f32 v51, v160, v161
	v_cvt_pk_bf16_f32 v50, v158, v159
	v_cvt_pk_bf16_f32 v49, v156, v157
	v_cvt_pk_bf16_f32 v48, v154, v155
	s_nop 1
	v_mfma_f32_32x32x16_bf16 v[32:47], v[56:59], v[48:51], v[32:47]
	s_waitcnt lgkmcnt(1)
	v_mfma_f32_32x32x16_bf16 v[16:31], v[52:55], v[48:51], v[16:31]
	ds_read_b128 v[48:51], v138 offset:20992
	s_waitcnt lgkmcnt(0)
	v_mfma_f32_32x32x16_bf16 v[48:63], v[48:51], v[2:5], 0
	v_mfma_f32_32x32x16_bf16 v[48:63], v[162:165], v[6:9], v[48:63]
	ds_read_b128 v[162:165], v140 offset:20992
	s_waitcnt lgkmcnt(0)
	v_mfma_f32_32x32x16_bf16 v[48:63], v[162:165], v[10:13], v[48:63]
	ds_read_b128 v[162:165], v145 offset:20992
	s_waitcnt lgkmcnt(0)
	v_mfma_f32_32x32x16_bf16 v[48:63], v[162:165], v[64:67], v[48:63]
	s_cbranch_vccnz .LBB0_772
	v_add_u32_e32 v138, 0x460, v141
	v_ashrrev_i32_e32 v139, 31, v138
	v_lshl_add_u64 v[162:163], v[138:139], 2, v[110:111]
	global_load_dwordx4 v[214:217], v[162:163], off offset:444
	global_load_dwordx4 v[218:221], v[162:163], off offset:476
	global_load_dwordx4 v[222:225], v[162:163], off offset:508
	global_load_dwordx4 v[226:229], v[162:163], off offset:540
	s_waitcnt vmcnt(0)
	s_nop 5
	v_add_f32_e32 v48, v48, v214
	v_add_f32_e32 v49, v49, v215
	v_add_f32_e32 v50, v50, v216
	v_add_f32_e32 v51, v51, v217
	v_cndmask_b32_e64 v48, v210, v48, s[46:47]
	v_cndmask_b32_e64 v49, v210, v49, s[80:81]
	v_cndmask_b32_e64 v50, v210, v50, s[82:83]
	v_cndmask_b32_e64 v51, v210, v51, s[84:85]
	v_add_f32_e32 v52, v52, v218
	v_add_f32_e32 v53, v53, v219
	v_add_f32_e32 v54, v54, v220
	v_add_f32_e32 v55, v55, v221
	v_cndmask_b32_e64 v52, v210, v52, s[86:87]
	v_cndmask_b32_e64 v53, v210, v53, s[88:89]
	v_cndmask_b32_e64 v54, v210, v54, s[90:91]
	v_cndmask_b32_e64 v55, v210, v55, s[92:93]
	v_add_f32_e32 v56, v56, v222
	v_add_f32_e32 v57, v57, v223
	v_add_f32_e32 v58, v58, v224
	v_add_f32_e32 v59, v59, v225
	v_cndmask_b32_e64 v56, v210, v56, s[94:95]
	v_cndmask_b32_e64 v57, v210, v57, s[96:97]
	v_cndmask_b32_e64 v58, v210, v58, s[40:41]
	v_cndmask_b32_e64 v59, v210, v59, s[6:7]
	v_add_f32_e32 v60, v60, v226
	v_add_f32_e32 v61, v61, v227
	v_add_f32_e32 v62, v62, v228
	v_add_f32_e32 v63, v63, v229
	v_cndmask_b32_e64 v60, v210, v60, s[8:9]
	v_cndmask_b32_e64 v61, v210, v61, s[10:11]
	v_cndmask_b32_e64 v62, v210, v62, s[12:13]
	v_cndmask_b32_e64 v63, v210, v63, s[14:15]
	s_branch .LBB0_772
